# down-GEMM last-panel tail: 4-way K split on 16 WGs (12/12/10/10 K-tiles, bf16 partials in the reserved WS_MXT slots, summed in f32 by the row phase) instead of 2-way on 8; dqkv rstd loads hoisted
# speedup vs baseline: 1.0124x; 1.0124x over previous
;     __device__ __forceinline__ bool next(int i, Unit& u) const { if (i > 0 || c >= nN) return false; u.pm = pm; u.pn = c; return true; }
; __device__ __forceinline__ KP kp_fresh(KP k) { asm volatile("" : "+s"(k)); return k; }
;     __host__ __device__ bool next(int i, Unit& u) const {
;         const long L = (long)i * G + c; if (L >= nwg) return false;
;         int wgid = (int)L; { const int q = nwg / NXCD, r = nwg % NXCD, xcd = wgid % NXCD, off = wgid / NXCD; wgid = (xcd < r ? xcd * (q + 1) : r * (q + 1) + (xcd - r) * q) + off; }
;         const int nig = wgm * nN, gid = wgid / nig, fm = gid * wgm, gsz = (nM - fm) < wgm ? (nM - fm) : wgm;
;         u.pm = fm + ((wgid % nig) % gsz); u.pn = (wgid % nig) / gsz; return true;
; __global__ void __launch_bounds__(512, 2) hybrid_fwd(Params p_unused) {
;     ...
;             const int ntail = half == 1 ? 8 : 4;
;             if (bid < ntail) {
;                 const int ks = bid >> 2;
;                 unsigned char* ws = kp_fresh(kp0)->ws;
;                 pg8::Gemm gt = g; bf16* mxo = (bf16*)(ws + WS_MX);
;                 if (half == 1) { gt.A = g.A + ks * (DFF / 2); gt.Bt = g.Bt + ks * (DFF / 2); gt.K = DFF / 2; mxo = (bf16*)(ws + WS_MXT) + (size_t)ks * 256 * 1024 - (size_t)128 * 256 * 1024; }
;                 pg8::TailOrder S{128, 4, bid & 3};
;                 pg8::EpiStore E{mxo, 1024, (half == 0 && (layer & 1)) ? (const float*)(ws + WS_RSTD) : nullptr, 0.f, nullptr, nullptr, nullptr, LL};
;                 pg8::gemm_phase<pg8::EpiStore, pg8::TailOrder, true, true>(lds, gt, S, E, wid0);
.LBB0_183:
	s_or_b64 exec, exec, s[2:3]
	s_sub_i32 s0, 0, s61
	s_barrier
	v_writelane_b32 v255, s0, 0
	s_load_dword s0, s[88:89], 0xe8
	s_mul_i32 s51, s39, s38
	s_cmpk_lt_i32 s33, 0x306
	s_movk_i32 s54, 0xf800
	s_movk_i32 s63, 0x50
	s_waitcnt lgkmcnt(0)
	s_mul_i32 s51, s51, s0
	s_cselect_b64 s[0:1], -1, 0
	v_writelane_b32 v255, s0, 1
	s_ashr_i32 s39, s33, 31
	s_ashr_i32 s50, s38, 31
	v_writelane_b32 v255, s1, 2
	s_lshr_b32 s0, s39, 29
	s_add_i32 s0, s33, s0
	s_ashr_i32 s4, s0, 3
	s_and_b32 s0, s0, -8
	s_sub_i32 s5, s33, s0
	s_mul_i32 s0, s5, 0x60
	s_or_b32 s6, s0, 6
	s_lshr_b32 s0, s38, 31
	s_add_i32 s0, s38, s0
	s_ashr_i32 s0, s0, 1
	s_add_i32 s7, s0, s33
	s_cmpk_lt_i32 s33, 0x100
	s_cselect_b64 s[0:1], -1, 0
	v_writelane_b32 v255, s0, 3
	s_cmpk_lt_i32 s33, 0xb42
	s_mov_b32 s62, 0xfe03f81
	v_writelane_b32 v255, s1, 4
	s_cselect_b64 s[0:1], -1, 0
	v_writelane_b32 v255, s0, 5
	v_mov_b32_e32 v242, 0x358637bd
	s_mov_b32 s80, 0xf800000
	v_writelane_b32 v255, s1, 6
	s_mul_i32 s0, s5, 0x168
	s_or_b32 s8, s0, 2
	s_cmpk_lt_i32 s33, 0x200
	s_cselect_b64 s[0:1], -1, 0
	v_writelane_b32 v255, s0, 7
	s_lshl_b32 s9, s5, 6
	v_mov_b32_e32 v243, 0x260
	v_writelane_b32 v255, s1, 8
	s_ashr_i32 s0, s33, 2
	s_ashr_i32 s1, s0, 31
	s_mul_i32 s2, s0, 0x300
	s_sub_i32 s3, s0, 2
	s_max_i32 s3, s3, 0
	s_lshl_b32 s3, s3, 7
	s_sub_i32 s2, s2, s3
	s_lshl_b64 s[0:1], s[0:1], 19
	v_writelane_b32 v255, s0, 9
	s_ashr_i32 s3, s2, 31
	s_movk_i32 s90, 0xc00
	v_writelane_b32 v255, s1, 10
	s_and_b32 s0, s33, 3
	v_writelane_b32 v255, s0, 11
	s_lshl_b32 s0, s0, 8
	v_writelane_b32 v255, s0, 12
	s_cmp_lt_i32 s5, 6
	s_mul_i32 s0, s5, 0x61
	s_cselect_b32 s0, s0, s6
	s_add_i32 s0, s0, s4
	s_mul_hi_i32 s1, s0, 0x2aaaaaab
	s_lshr_b32 s6, s1, 31
	s_ashr_i32 s1, s1, 3
	s_add_i32 s1, s1, s6
	s_lshl_b32 s6, s1, 3
	s_sub_i32 s10, 0x81, s6
	s_mul_i32 s1, s1, 48
	s_min_u32 s10, s10, 8
	s_sub_i32 s11, s0, s1
	s_cmp_lt_i32 s5, 2
	s_mul_i32 s0, s5, 0x169
	s_cselect_b32 s0, s0, s8
	s_add_i32 s0, s0, s4
	s_mul_hi_i32 s1, s0, 0x2e8ba2e9
	s_lshr_b32 s8, s1, 31
	s_ashr_i32 s1, s1, 4
	s_add_i32 s1, s1, s8
	s_lshl_b32 s8, s1, 2
	s_sub_i32 s12, 0x83, s8
	s_mulk_i32 s1, 0x58
	s_min_u32 s12, s12, 4
	s_sub_i32 s13, s0, s1
	s_cmp_lt_i32 s5, 0
	s_mulk_i32 s5, 0x41
	s_cselect_b32 s0, s5, s9
	s_add_i32 s0, s0, s4
	s_ashr_i32 s1, s0, 31
	s_lshr_b32 s1, s1, 27
	s_add_i32 s1, s0, s1
	s_ashr_i32 s4, s1, 5
	s_and_b32 s1, s1, 0xffe0
	s_sub_i32 s1, s0, s1
	s_bfe_i32 s0, s1, 0x80000
	s_bfe_u32 s0, s0, 0x3000c
	s_add_i32 s5, s1, s0
	s_bfe_i32 s0, s5, 0x80000
	s_and_b32 s5, s5, 0xf8
	v_cvt_f32_ubyte0_e32 v1, s10
	s_sub_i32 s1, s1, s5
	v_cvt_f32_i32_e32 v0, s11
	v_rcp_iflag_f32_e32 v2, v1
	s_lshl_b32 s4, s4, 3
	s_sext_i32_i8 s1, s1
	s_sext_i32_i16 s9, s0
	s_add_i32 s1, s4, s1
	s_lshr_b32 s0, s9, 3
	v_writelane_b32 v255, s1, 13
	s_ashr_i32 s1, s9, 3
	v_writelane_b32 v255, s1, 14
	s_bfe_i64 s[0:1], s[0:1], 0x100000
	v_mul_f32_e32 v2, v0, v2
	v_writelane_b32 v255, s0, 15
	v_trunc_f32_e32 v2, v2
	v_fma_f32 v0, -v2, v1, v0
	v_writelane_b32 v255, s1, 16
	s_ashr_i32 s0, s11, 30
	s_or_b32 s4, s0, 1
	v_cmp_ge_f32_e64 s[0:1], |v0|, v1
	s_and_b64 s[0:1], s[0:1], exec
	s_cselect_b32 s0, s4, 0
	s_abs_i32 s1, s38
	v_cvt_f32_u32_e32 v0, s1
	v_cvt_i32_f32_e32 v2, v2
	s_abs_i32 s5, s7
	s_mov_b32 s81, 0xffff0000
	v_rcp_iflag_f32_e32 v0, v0
	v_readfirstlane_b32 s4, v2
	s_add_i32 s0, s4, s0
	s_mul_i32 s4, s0, s10
	v_mul_f32_e32 v0, 0x4f7ffffe, v0
	v_cvt_u32_f32_e32 v0, v0
	s_sub_i32 s4, s11, s4
	s_sext_i32_i8 s4, s4
	s_add_i32 s4, s6, s4
	v_writelane_b32 v255, s4, 17
	s_ashr_i32 s4, s7, 31
	s_sub_i32 s6, 0, s1
	v_readfirstlane_b32 s7, v0
	s_mul_i32 s6, s6, s7
	s_mul_hi_u32 s6, s7, s6
	s_add_i32 s7, s7, s6
	s_mul_hi_u32 s6, s5, s7
	s_mul_i32 s6, s6, s1
	s_sub_i32 s5, s5, s6
	s_sub_i32 s6, s5, s1
	s_cmp_ge_u32 s5, s1
	s_cselect_b32 s5, s6, s5
	s_sub_i32 s6, s5, s1
	s_cmp_ge_u32 s5, s1
	s_cselect_b32 s1, s6, s5
	s_xor_b32 s1, s1, s4
	s_sub_i32 s5, s1, s4
	s_cmpk_lt_i32 s5, 0x408
	s_cselect_b64 s[6:7], -1, 0
	v_writelane_b32 v255, s6, 18
	s_ashr_i32 s1, s5, 31
	s_sext_i32_i8 s0, s0
	v_writelane_b32 v255, s7, 19
	v_writelane_b32 v255, s1, 20
	s_lshr_b32 s1, s1, 29
	s_add_i32 s1, s5, s1
	s_ashr_i32 s4, s1, 3
	s_and_b32 s1, s1, -8
	s_sub_i32 s1, s5, s1
	v_writelane_b32 v255, s5, 21
	s_cmp_lt_i32 s1, 0
	s_movk_i32 s5, 0x82
	s_cselect_b32 s5, s5, 0x81
	s_mul_i32 s1, s1, s5
	s_add_i32 s1, s1, s4
	s_ashr_i32 s4, s1, 31
	s_lshr_b32 s4, s4, 26
	s_add_i32 s4, s1, s4
	s_ashr_i32 s5, s4, 6
	s_lshl_b32 s5, s5, 3
	s_sub_i32 s6, 0x81, s5
	s_min_u32 s6, s6, 8
	s_andn2_b32 s4, s4, 63
	s_sub_i32 s4, s1, s4
	v_cvt_f32_ubyte0_e32 v1, s6
	v_cvt_f32_i32_e32 v0, s4
	v_rcp_iflag_f32_e32 v2, v1
	v_writelane_b32 v255, s0, 22
	s_ashr_i32 s0, s4, 30
	s_or_b32 s7, s0, 1
	v_mul_f32_e32 v2, v0, v2
	v_trunc_f32_e32 v2, v2
	v_fma_f32 v0, -v2, v1, v0
	v_cvt_i32_f32_e32 v2, v2
	v_cmp_ge_f32_e64 s[0:1], |v0|, v1
	s_and_b64 s[0:1], s[0:1], exec
	s_cselect_b32 s0, s7, 0
	v_readfirstlane_b32 s1, v2
	s_add_i32 s0, s1, s0
	s_sext_i32_i8 s1, s0
	v_cvt_f32_ubyte0_e32 v1, s12
	v_writelane_b32 v255, s1, 23
	s_mul_i32 s1, s0, s6
	v_cvt_f32_i32_e32 v0, s13
	v_rcp_iflag_f32_e32 v2, v1
	s_sub_i32 s1, s4, s1
	s_sext_i32_i8 s1, s1
	s_add_i32 s1, s5, s1
	v_writelane_b32 v255, s1, 24
	s_bfe_i64 s[0:1], s[0:1], 0x80000
	v_mul_f32_e32 v2, v0, v2
	s_lshl_b64 s[0:1], s[0:1], 17
	v_trunc_f32_e32 v2, v2
	v_writelane_b32 v255, s0, 25
	v_fma_f32 v0, -v2, v1, v0
	v_cvt_i32_f32_e32 v2, v2
	v_writelane_b32 v255, s1, 26
	s_ashr_i32 s0, s13, 30
	s_or_b32 s4, s0, 1
	v_cmp_ge_f32_e64 s[0:1], |v0|, v1
	s_and_b64 s[0:1], s[0:1], exec
	s_cselect_b32 s0, s4, 0
	v_readfirstlane_b32 s1, v2
	s_add_i32 s0, s1, s0
	s_sext_i32_i8 s1, s0
	s_mul_i32 s0, s0, s12
	s_sub_i32 s0, s13, s0
	s_sext_i32_i8 s0, s0
	v_writelane_b32 v255, s1, 27
	s_add_i32 s0, s8, s0
	v_writelane_b32 v255, s0, 28
	s_add_u32 s0, s33, s38
	s_addc_u32 s1, s39, s50
	v_writelane_b32 v255, s0, 29
	v_mov_b32_e32 v0, 0
	s_mov_b32 s52, 0xff800000
	v_writelane_b32 v255, s1, 30
	s_lshl_b32 s0, s33, 4
	s_or_b32 s0, s0, 8
	v_writelane_b32 v255, s0, 31
	s_add_i32 s0, 0, 0x25f00
	v_writelane_b32 v255, s0, 32
	s_add_i32 s0, 0, 0x25f04
	v_writelane_b32 v255, s0, 33
	s_add_i32 s0, 0, 0x24400
	v_writelane_b32 v255, s0, 34
	s_add_i32 s0, 0, 0x20400
	v_writelane_b32 v255, s0, 35
	s_lshl_b64 s[0:1], s[2:3], 1
	v_writelane_b32 v255, s0, 36
	s_mov_b32 s53, 0x41000000
	v_mov_b32_e32 v244, 0xff800000
	v_writelane_b32 v255, s1, 37
	v_writelane_b32 v255, s88, 38
	v_mov_b32_e32 v245, 0x80ff
	s_mov_b32 s42, 0x8100
	v_writelane_b32 v255, s89, 39
	s_movk_i32 s84, 0xf7f0
	s_mov_b32 s0, 0
	s_mov_b32 s87, 0
	s_mov_b64 s[64:65], 0x20000
	s_mov_b64 s[66:67], 0x40000
	s_mov_b64 s[68:69], 0x60000
	s_mov_b64 s[70:71], 0x80
	s_mov_b64 s[72:73], 0x20080
	s_mov_b64 s[74:75], 0x40080
	s_mov_b64 s[76:77], 0x60080
	s_mov_b64 s[92:93], 0x48080
	s_mov_b64 s[96:97], 0x8000
	s_mov_b32 s55, -1
	v_writelane_b32 v255, s61, 40
	s_branch .LBB0_185

; __device__ __forceinline__ unsigned cvt_pk_bf16(float lo, float hi) { unsigned r; asm volatile("v_cvt_pk_bf16_f32 %0, %1, %2" : "=v"(r) : "v"(lo), "v"(hi)); return r; }
;     __device__ __forceinline__ void operator()(const f32x4 (&acc)[2][2][4][2], const Unit& u, int wr, int wc, int fr_, int fq_) const {
;     ...
;             for (int m = 0; m < 4; ++m) { const int row = row0 + ai * HALF + m * 16; bf16_t* rowp = O + (size_t)row * 768 + col0; const float sc = rs[row];
; #pragma unroll
;                 for (int bj = 0; bj < 2; ++bj) { const f32x4 v0 = acc[ai][bj][m][0] * sc, v1 = acc[ai][bj][m][1] * sc;
;                     u32x4 w; w.x = cvt_pk_bf16(v0[0], v0[1]); w.y = cvt_pk_bf16(v0[2], v0[3]); w.z = cvt_pk_bf16(v1[0], v1[1]); w.w = cvt_pk_bf16(v1[2], v1[3]);
;                     *(u32x4*)(rowp + bj * HALF) = w;
;                     float p = v0[0] * v0[0] + v0[1] * v0[1] + v0[2] * v0[2] + v0[3] * v0[3] + v1[0] * v1[0] + v1[1] * v1[1] + v1[2] * v1[2] + v1[3] * v1[3];
;                     p += __int_as_float(__builtin_amdgcn_ds_bpermute((l_ ^ 16) << 2, __float_as_int(p)));
;                     p += __int_as_float(__builtin_amdgcn_ds_bpermute((l_ ^ 32) << 2, __float_as_int(p)));
;                     const int kind = bj == 0 ? kind0 : kind1;
;                     const int slot = kind == 0 ? (u.pn == 0 ? bj * 4 + wc : 8 + wc) : 12 + (u.pn == 1 ? wc : 4 + wc);
;                     if (fq == 0 && kind < 2) ps[(size_t)row * 20 + slot] = p; } }
.LBB0_208:
	v_mbcnt_lo_u32_b32 v140, -1, 0
	v_mbcnt_hi_u32_b32 v140, -1, v140
	s_lshl_b32 s17, s4, 8
	v_and_or_b32 v136, v140, 15, s48
	v_lshl_add_u32 v136, s24, 8, v136
	v_ashrrev_i32_e32 v137, 31, v136
	v_lshl_add_u64 v[138:139], v[136:137], 2, s[10:11]
	global_load_dword v144, v[138:139], off
	global_load_dword v208, v[138:139], off offset:64
	global_load_dword v209, v[138:139], off offset:128
	global_load_dword v210, v[138:139], off offset:192
	v_lshlrev_b32_e32 v141, 2, v140
	v_xor_b32_e32 v147, 64, v141
	v_ashrrev_i32_e32 v137, 1, v140
	v_cmp_gt_u32_e32 vcc, 16, v140
	v_and_b32_e32 v140, -8, v137
	v_xor_b32_e32 v137, 0x80, v141
	s_or_b32 s17, s17, s49
	v_mov_b64_e32 v[142:143], s[8:9]
	s_cmp_eq_u32 s4, 2
	v_add_u32_e32 v140, s17, v140
	s_movk_i32 s17, 0x600
	s_cselect_b64 s[26:27], -1, 0
	s_cmp_eq_u32 s4, 0
	v_mad_i64_i32 v[142:143], s[24:25], v136, s17, v[142:143]
	v_ashrrev_i32_e32 v141, 31, v140
	v_mad_i64_i32 v[150:151], s[28:29], v136, s63, 0
	s_cselect_b64 s[24:25], -1, 0
	v_lshl_add_u64 v[142:143], v[140:141], 1, v[142:143]
	s_waitcnt vmcnt(0)
	v_pk_mul_f32 v[126:127], v[126:127], v[144:145] op_sel_hi:[1,0]
	v_pk_mul_f32 v[148:149], v[124:125], v[144:145] op_sel_hi:[1,0]
	v_mul_f32_e32 v124, v127, v127
	v_pk_mul_f32 v[128:129], v[128:129], v[144:145] op_sel_hi:[1,0]
	v_fmac_f32_e32 v124, v126, v126
	v_fmac_f32_e32 v124, v128, v128
	v_pk_mul_f32 v[122:123], v[122:123], v[144:145] op_sel_hi:[1,0]
	v_fmac_f32_e32 v124, v129, v129
	v_fmac_f32_e32 v124, v122, v122
	v_fmac_f32_e32 v124, v123, v123
	v_fmac_f32_e32 v124, v148, v148
	v_fmac_f32_e32 v124, v149, v149
	ds_bpermute_b32 v125, v147, v124
	v_cvt_pk_bf16_f32 v126, v126, v127
	v_cvt_pk_bf16_f32 v127, v128, v129
	v_cvt_pk_bf16_f32 v128, v122, v123
	v_lshl_add_u64 v[122:123], s[12:13], 0, v[150:151]
	s_waitcnt lgkmcnt(0)
	v_add_f32_e32 v124, v124, v125
	ds_bpermute_b32 v125, v137, v124
	v_cvt_pk_bf16_f32 v129, v148, v149
	global_store_dwordx4 v[142:143], v[126:129], off
	s_and_saveexec_b64 s[28:29], vcc
	s_cbranch_execz .LBB0_210
	s_and_b64 s[30:31], s[24:25], exec
	s_cselect_b32 s17, s47, s57
	s_and_b64 s[30:31], s[26:27], exec
	s_cselect_b32 s17, s58, s17
	s_lshl_b32 s86, s17, 2
	v_lshl_add_u64 v[126:127], v[122:123], 0, s[86:87]
	s_waitcnt lgkmcnt(0)
	v_add_f32_e32 v124, v124, v125
	global_store_dword v[126:127], v124, off

; __device__ __forceinline__ unsigned cvt_pk_bf16(float lo, float hi) { unsigned r; asm volatile("v_cvt_pk_bf16_f32 %0, %1, %2" : "=v"(r) : "v"(lo), "v"(hi)); return r; }
;     __device__ __forceinline__ void operator()(const f32x4 (&acc)[2][2][4][2], const Unit& u, int wr, int wc, int fr_, int fq_) const {
;     ...
;             for (int m = 0; m < 4; ++m) { const int row = row0 + ai * HALF + m * 16; bf16_t* rowp = O + (size_t)row * 768 + col0; const float sc = rs[row];
; #pragma unroll
;                 for (int bj = 0; bj < 2; ++bj) { const f32x4 v0 = acc[ai][bj][m][0] * sc, v1 = acc[ai][bj][m][1] * sc;
;                     u32x4 w; w.x = cvt_pk_bf16(v0[0], v0[1]); w.y = cvt_pk_bf16(v0[2], v0[3]); w.z = cvt_pk_bf16(v1[0], v1[1]); w.w = cvt_pk_bf16(v1[2], v1[3]);
;                     *(u32x4*)(rowp + bj * HALF) = w;
;                     float p = v0[0] * v0[0] + v0[1] * v0[1] + v0[2] * v0[2] + v0[3] * v0[3] + v1[0] * v1[0] + v1[1] * v1[1] + v1[2] * v1[2] + v1[3] * v1[3];
;                     p += __int_as_float(__builtin_amdgcn_ds_bpermute((l_ ^ 16) << 2, __float_as_int(p)));
;                     p += __int_as_float(__builtin_amdgcn_ds_bpermute((l_ ^ 32) << 2, __float_as_int(p)));
;                     const int kind = bj == 0 ? kind0 : kind1;
;                     const int slot = kind == 0 ? (u.pn == 0 ? bj * 4 + wc : 8 + wc) : 12 + (u.pn == 1 ? wc : 4 + wc);
;                     if (fq == 0 && kind < 2) ps[(size_t)row * 20 + slot] = p; } }
.LBB0_212:
	s_or_b64 exec, exec, s[30:31]
	v_or_b32_e32 v118, 16, v136
	v_ashrrev_i32_e32 v119, 31, v118
	s_waitcnt lgkmcnt(0)
	v_mov_b32_e32 v116, v208
	v_mov_b64_e32 v[114:115], s[8:9]
	s_movk_i32 s17, 0x600
	v_mad_i64_i32 v[114:115], s[30:31], v118, s17, v[114:115]
	v_mad_i64_i32 v[118:119], s[30:31], v118, s63, 0
	v_lshl_add_u64 v[114:115], v[140:141], 1, v[114:115]
	s_waitcnt vmcnt(0)
	v_pk_mul_f32 v[110:111], v[110:111], v[116:117] op_sel_hi:[1,0]
	v_pk_mul_f32 v[120:121], v[108:109], v[116:117] op_sel_hi:[1,0]
	v_mul_f32_e32 v108, v111, v111
	v_pk_mul_f32 v[112:113], v[112:113], v[116:117] op_sel_hi:[1,0]
	v_fmac_f32_e32 v108, v110, v110
	v_fmac_f32_e32 v108, v112, v112
	v_pk_mul_f32 v[106:107], v[106:107], v[116:117] op_sel_hi:[1,0]
	v_fmac_f32_e32 v108, v113, v113
	v_fmac_f32_e32 v108, v106, v106
	v_fmac_f32_e32 v108, v107, v107
	v_fmac_f32_e32 v108, v120, v120
	v_fmac_f32_e32 v108, v121, v121
	ds_bpermute_b32 v109, v147, v108
	v_cvt_pk_bf16_f32 v110, v110, v111
	v_cvt_pk_bf16_f32 v111, v112, v113
	v_cvt_pk_bf16_f32 v112, v106, v107
	v_lshl_add_u64 v[106:107], s[12:13], 0, v[118:119]
	s_waitcnt lgkmcnt(0)
	v_add_f32_e32 v108, v108, v109
	ds_bpermute_b32 v109, v137, v108
	v_cvt_pk_bf16_f32 v113, v120, v121
	global_store_dwordx4 v[114:115], v[110:113], off
	s_and_saveexec_b64 s[30:31], vcc
	v_readlane_b32 s88, v255, 38
	v_readlane_b32 s89, v255, 39
	s_cbranch_execz .LBB0_214
	s_and_b64 s[78:79], s[24:25], exec
	s_cselect_b32 s17, s47, s57
	s_and_b64 s[78:79], s[26:27], exec
	s_cselect_b32 s17, s58, s17
	s_lshl_b32 s86, s17, 2
	v_lshl_add_u64 v[110:111], v[106:107], 0, s[86:87]
	s_waitcnt lgkmcnt(0)
	v_add_f32_e32 v108, v108, v109
	global_store_dword v[110:111], v108, off

; __device__ __forceinline__ unsigned cvt_pk_bf16(float lo, float hi) { unsigned r; asm volatile("v_cvt_pk_bf16_f32 %0, %1, %2" : "=v"(r) : "v"(lo), "v"(hi)); return r; }
;     __device__ __forceinline__ void operator()(const f32x4 (&acc)[2][2][4][2], const Unit& u, int wr, int wc, int fr_, int fq_) const {
;     ...
;             for (int m = 0; m < 4; ++m) { const int row = row0 + ai * HALF + m * 16; bf16_t* rowp = O + (size_t)row * 768 + col0; const float sc = rs[row];
; #pragma unroll
;                 for (int bj = 0; bj < 2; ++bj) { const f32x4 v0 = acc[ai][bj][m][0] * sc, v1 = acc[ai][bj][m][1] * sc;
;                     u32x4 w; w.x = cvt_pk_bf16(v0[0], v0[1]); w.y = cvt_pk_bf16(v0[2], v0[3]); w.z = cvt_pk_bf16(v1[0], v1[1]); w.w = cvt_pk_bf16(v1[2], v1[3]);
;                     *(u32x4*)(rowp + bj * HALF) = w;
;                     float p = v0[0] * v0[0] + v0[1] * v0[1] + v0[2] * v0[2] + v0[3] * v0[3] + v1[0] * v1[0] + v1[1] * v1[1] + v1[2] * v1[2] + v1[3] * v1[3];
;                     p += __int_as_float(__builtin_amdgcn_ds_bpermute((l_ ^ 16) << 2, __float_as_int(p)));
;                     p += __int_as_float(__builtin_amdgcn_ds_bpermute((l_ ^ 32) << 2, __float_as_int(p)));
;                     const int kind = bj == 0 ? kind0 : kind1;
;                     const int slot = kind == 0 ? (u.pn == 0 ? bj * 4 + wc : 8 + wc) : 12 + (u.pn == 1 ? wc : 4 + wc);
;                     if (fq == 0 && kind < 2) ps[(size_t)row * 20 + slot] = p; } }
.LBB0_216:
	s_or_b64 exec, exec, s[30:31]
	v_or_b32_e32 v102, 32, v136
	v_ashrrev_i32_e32 v103, 31, v102
	s_waitcnt lgkmcnt(0)
	v_mov_b32_e32 v100, v209
	v_mov_b64_e32 v[98:99], s[8:9]
	s_movk_i32 s17, 0x600
	v_mad_i64_i32 v[98:99], s[30:31], v102, s17, v[98:99]
	v_mad_i64_i32 v[102:103], s[30:31], v102, s63, 0
	v_lshl_add_u64 v[98:99], v[140:141], 1, v[98:99]
	s_waitcnt vmcnt(0)
	v_pk_mul_f32 v[94:95], v[94:95], v[100:101] op_sel_hi:[1,0]
	v_pk_mul_f32 v[104:105], v[92:93], v[100:101] op_sel_hi:[1,0]
	v_mul_f32_e32 v92, v95, v95
	v_pk_mul_f32 v[96:97], v[96:97], v[100:101] op_sel_hi:[1,0]
	v_fmac_f32_e32 v92, v94, v94
	v_fmac_f32_e32 v92, v96, v96
	v_pk_mul_f32 v[90:91], v[90:91], v[100:101] op_sel_hi:[1,0]
	v_fmac_f32_e32 v92, v97, v97
	v_fmac_f32_e32 v92, v90, v90
	v_fmac_f32_e32 v92, v91, v91
	v_fmac_f32_e32 v92, v104, v104
	v_fmac_f32_e32 v92, v105, v105
	ds_bpermute_b32 v93, v147, v92
	v_cvt_pk_bf16_f32 v94, v94, v95
	v_cvt_pk_bf16_f32 v95, v96, v97
	v_cvt_pk_bf16_f32 v96, v90, v91
	v_lshl_add_u64 v[90:91], s[12:13], 0, v[102:103]
	s_waitcnt lgkmcnt(0)
	v_add_f32_e32 v92, v92, v93
	ds_bpermute_b32 v93, v137, v92
	v_cvt_pk_bf16_f32 v97, v104, v105
	global_store_dwordx4 v[98:99], v[94:97], off
	s_and_saveexec_b64 s[30:31], vcc
	s_cbranch_execz .LBB0_218
	s_and_b64 s[78:79], s[24:25], exec
	s_cselect_b32 s17, s47, s57
	s_and_b64 s[78:79], s[26:27], exec
	s_cselect_b32 s17, s58, s17
	s_lshl_b32 s86, s17, 2
	v_lshl_add_u64 v[94:95], v[90:91], 0, s[86:87]
	s_waitcnt lgkmcnt(0)
	v_add_f32_e32 v92, v92, v93
	global_store_dword v[94:95], v92, off

; __device__ __forceinline__ unsigned cvt_pk_bf16(float lo, float hi) { unsigned r; asm volatile("v_cvt_pk_bf16_f32 %0, %1, %2" : "=v"(r) : "v"(lo), "v"(hi)); return r; }
;     __device__ __forceinline__ void operator()(const f32x4 (&acc)[2][2][4][2], const Unit& u, int wr, int wc, int fr_, int fq_) const {
;     ...
;             for (int m = 0; m < 4; ++m) { const int row = row0 + ai * HALF + m * 16; bf16_t* rowp = O + (size_t)row * 768 + col0; const float sc = rs[row];
; #pragma unroll
;                 for (int bj = 0; bj < 2; ++bj) { const f32x4 v0 = acc[ai][bj][m][0] * sc, v1 = acc[ai][bj][m][1] * sc;
;                     u32x4 w; w.x = cvt_pk_bf16(v0[0], v0[1]); w.y = cvt_pk_bf16(v0[2], v0[3]); w.z = cvt_pk_bf16(v1[0], v1[1]); w.w = cvt_pk_bf16(v1[2], v1[3]);
;                     *(u32x4*)(rowp + bj * HALF) = w;
;                     float p = v0[0] * v0[0] + v0[1] * v0[1] + v0[2] * v0[2] + v0[3] * v0[3] + v1[0] * v1[0] + v1[1] * v1[1] + v1[2] * v1[2] + v1[3] * v1[3];
;                     p += __int_as_float(__builtin_amdgcn_ds_bpermute((l_ ^ 16) << 2, __float_as_int(p)));
;                     p += __int_as_float(__builtin_amdgcn_ds_bpermute((l_ ^ 32) << 2, __float_as_int(p)));
;                     const int kind = bj == 0 ? kind0 : kind1;
;                     const int slot = kind == 0 ? (u.pn == 0 ? bj * 4 + wc : 8 + wc) : 12 + (u.pn == 1 ? wc : 4 + wc);
;                     if (fq == 0 && kind < 2) ps[(size_t)row * 20 + slot] = p; } }
.LBB0_220:
	s_or_b64 exec, exec, s[30:31]
	v_or_b32_e32 v86, 48, v136
	v_ashrrev_i32_e32 v87, 31, v86
	s_waitcnt lgkmcnt(0)
	v_mov_b32_e32 v84, v210
	v_mov_b64_e32 v[82:83], s[8:9]
	s_movk_i32 s17, 0x600
	v_mad_i64_i32 v[82:83], s[30:31], v86, s17, v[82:83]
	v_mad_i64_i32 v[86:87], s[30:31], v86, s63, 0
	v_lshl_add_u64 v[82:83], v[140:141], 1, v[82:83]
	s_waitcnt vmcnt(0)
	v_pk_mul_f32 v[78:79], v[78:79], v[84:85] op_sel_hi:[1,0]
	v_pk_mul_f32 v[88:89], v[76:77], v[84:85] op_sel_hi:[1,0]
	v_mul_f32_e32 v76, v79, v79
	v_pk_mul_f32 v[80:81], v[80:81], v[84:85] op_sel_hi:[1,0]
	v_fmac_f32_e32 v76, v78, v78
	v_fmac_f32_e32 v76, v80, v80
	v_pk_mul_f32 v[74:75], v[74:75], v[84:85] op_sel_hi:[1,0]
	v_fmac_f32_e32 v76, v81, v81
	v_fmac_f32_e32 v76, v74, v74
	v_fmac_f32_e32 v76, v75, v75
	v_fmac_f32_e32 v76, v88, v88
	v_fmac_f32_e32 v76, v89, v89
	ds_bpermute_b32 v77, v147, v76
	v_cvt_pk_bf16_f32 v78, v78, v79
	v_cvt_pk_bf16_f32 v79, v80, v81
	v_cvt_pk_bf16_f32 v80, v74, v75
	v_lshl_add_u64 v[74:75], s[12:13], 0, v[86:87]
	s_waitcnt lgkmcnt(0)
	v_add_f32_e32 v76, v76, v77
	ds_bpermute_b32 v77, v137, v76
	v_cvt_pk_bf16_f32 v81, v88, v89
	global_store_dwordx4 v[82:83], v[78:81], off
	s_and_saveexec_b64 s[30:31], vcc
	s_cbranch_execz .LBB0_222
	s_and_b64 s[78:79], s[24:25], exec
	s_cselect_b32 s17, s47, s57
	s_and_b64 s[78:79], s[26:27], exec
	s_cselect_b32 s17, s58, s17
	s_lshl_b32 s86, s17, 2
	v_lshl_add_u64 v[78:79], v[74:75], 0, s[86:87]
	s_waitcnt lgkmcnt(0)
	v_add_f32_e32 v76, v76, v77
	global_store_dword v[78:79], v76, off

; __device__ __forceinline__ KP kp_fresh(KP k) { asm volatile("" : "+s"(k)); return k; }
; __device__ __forceinline__ int tid_fresh(int wid) { return wid * 64 + lane_id(); }
; __global__ void __launch_bounds__(512, 2) hybrid_fwd(Params p_unused) {
;     ...
;             const int gpi = half == 0 ? 3 : 5; const bool hn = half == 0 ? true : (layer + 1 < DEPTH);
;             const int ntail = half == 1 ? 8 : 4;
;             if (bid < ntail) {
;                 const int ks = bid >> 2;
;                 unsigned char* ws = kp_fresh(kp0)->ws;
;                 pg8::Gemm gt = g; bf16* mxo = (bf16*)(ws + WS_MX);
;                 if (half == 1) { gt.A = g.A + ks * (DFF / 2); gt.Bt = g.Bt + ks * (DFF / 2); gt.K = DFF / 2; mxo = (bf16*)(ws + WS_MXT) + (size_t)ks * 256 * 1024 - (size_t)128 * 256 * 1024; }
;                 pg8::TailOrder S{128, 4, bid & 3};
;                 pg8::EpiStore E{mxo, 1024, (half == 0 && (layer & 1)) ? (const float*)(ws + WS_RSTD) : nullptr, 0.f, nullptr, nullptr, nullptr, LL};
;                 pg8::gemm_phase<pg8::EpiStore, pg8::TailOrder, true, true>(lds, gt, S, E, wid0);
;                 tail_barrier((unsigned*)kp_fresh(kp0)->ws + 3584 + 64 * (layer * 2 + half), tid_fresh(wid0), (unsigned)ntail);
;                 const int rpb = 256 / ntail;
;                 row_res(kp0, gpi, layer, hn, wid0, 128 * 256 + rpb * bid, 128 * 256 + rpb * bid + rpb, bid, 1, half == 1 ? 2 : 0, half == 0 && (layer & 1));
;             } else {
;                 row_res(kp0, gpi, layer, hn, wid0, 0, 128 * 256, ntail, G - ntail, 0, half == 0 && (layer & 1));
.LBB0_773:
	s_or_b64 exec, exec, s[2:3]
	s_and_b64 s[2:3], s[28:29], exec
	v_readlane_b32 s2, v255, 49
	v_readlane_b32 s3, v255, 50
	s_cselect_b32 s17, 3, 5
	s_nor_b64 s[34:35], s[2:3], s[28:29]
	s_and_b64 s[2:3], s[24:25], exec
	s_cselect_b32 s18, 16, 4
	s_cmp_ge_i32 s33, s18
	s_mov_b64 s[2:3], -1
	s_waitcnt lgkmcnt(0)
	s_barrier
	s_cbranch_scc0 .LBB0_822
	s_mov_b64 s[2:3], s[88:89]
	v_mbcnt_lo_u32_b32 v1, -1, 0
	v_mbcnt_hi_u32_b32 v1, -1, v1
	s_sub_i32 s4, s33, s18
	v_add_u32_e32 v2, s61, v1
	v_ashrrev_i32_e32 v2, 6, v2
	v_lshl_add_u32 v38, s4, 4, v2
	s_mov_b32 s4, 0x8000
	v_cmp_gt_i32_e32 vcc, s4, v38
	s_and_saveexec_b64 s[44:45], vcc
	s_cbranch_execz .LBB0_821
	s_load_dwordx4 s[8:11], s[2:3], 0x90
	v_readlane_b32 s4, v255, 51
	v_readlane_b32 s5, v255, 52
	s_and_b64 s[4:5], s[4:5], s[28:29]
	s_xor_b64 s[78:79], s[4:5], -1
	s_waitcnt lgkmcnt(0)
	s_add_u32 s92, s10, 0x180000
	s_addc_u32 s93, s11, 0
	s_lshl_b32 s4, s17, 3
	s_load_dwordx2 s[2:3], s[2:3], s4 offset:0x0
	v_readlane_b32 s4, v255, 53
	v_readlane_b32 s5, v255, 54
	v_and_b32_e32 v3, 63, v1
	s_sub_i32 s14, s38, s18
	s_lshl_b64 s[4:5], s[4:5], 2
	v_lshlrev_b32_e32 v4, 4, v3
	s_waitcnt lgkmcnt(0)
	s_add_u32 s4, s2, s4
	v_mov_b32_e32 v5, v0
	s_addc_u32 s5, s3, s5
	s_waitcnt vmcnt(2)
	v_lshl_add_u64 v[6:7], s[10:11], 0, v[4:5]
	s_mov_b64 s[2:3], 0x18f74000
	v_lshl_add_u64 v[42:43], v[6:7], 0, s[2:3]
	s_mov_b64 s[2:3], 0x10e74000
	v_lshl_add_u64 v[44:45], v[6:7], 0, s[2:3]
	v_bfe_u32 v6, v1, 5, 1
	v_lshlrev_b32_e64 v1, v6, 2
	v_lshlrev_b32_e64 v41, v6, 8
	v_lshlrev_b32_e32 v6, 2, v3
	s_lshl_b32 s46, s14, 4
	v_xor_b32_e32 v101, 0x80, v6
	v_xor_b32_e32 v102, 64, v6
	v_xor_b32_e32 v103, 32, v6
	v_xor_b32_e32 v104, 16, v6
	v_xor_b32_e32 v105, 8, v6
	v_xor_b32_e32 v106, 4, v6
	v_lshlrev_b32_e32 v6, 5, v3
	v_mov_b32_e32 v7, v0
	v_lshl_add_u64 v[46:47], s[4:5], 0, v[6:7]
	s_add_u32 s4, s10, 0x10e73800
	v_ashrrev_i32_e32 v39, 31, v38
	s_addc_u32 s5, s11, 0
	v_lshlrev_b64 v[6:7], 11, v[38:39]
	s_ashr_i32 s47, s46, 31
	v_or_b32_e32 v6, v6, v4
	s_lshl_b64 s[58:59], s[46:47], 11
	v_lshl_add_u64 v[48:49], s[4:5], 0, v[6:7]
	s_add_u32 s10, s10, 0x10e73c00
	v_lshl_add_u64 v[52:53], s[4:5], 0, v[4:5]
	v_readlane_b32 s4, v255, 31
	s_addc_u32 s11, s11, 0
	v_lshlrev_b32_e32 v40, 3, v3
	v_add_u32_e32 v2, s4, v2
	s_lshl_b32 s4, s18, 4
	v_cmp_eq_u32_e64 s[2:3], 0, v3
	v_lshl_add_u64 v[50:51], s[10:11], 0, v[6:7]
	v_subrev_u32_e32 v54, s4, v2
	v_lshl_add_u64 v[56:57], s[10:11], 0, v[4:5]
	s_mov_b64 s[10:11], 0
	s_branch .LBB0_778

; __device__ __forceinline__ KP kp_fresh(KP k) { asm volatile("" : "+s"(k)); return k; }
; __global__ void __launch_bounds__(512, 2) hybrid_fwd(Params p_unused) {
;     ...
;             if (bid < ntail) {
;                 const int ks = bid >> 2;
;                 unsigned char* ws = kp_fresh(kp0)->ws;
;                 pg8::Gemm gt = g; bf16* mxo = (bf16*)(ws + WS_MX);
;                 if (half == 1) { gt.A = g.A + ks * (DFF / 2); gt.Bt = g.Bt + ks * (DFF / 2); gt.K = DFF / 2; mxo = (bf16*)(ws + WS_MXT) + (size_t)ks * 256 * 1024 - (size_t)128 * 256 * 1024; }
;                 pg8::TailOrder S{128, 4, bid & 3};
;                 pg8::EpiStore E{mxo, 1024, (half == 0 && (layer & 1)) ? (const float*)(ws + WS_RSTD) : nullptr, 0.f, nullptr, nullptr, nullptr, LL};
;                 pg8::gemm_phase<pg8::EpiStore, pg8::TailOrder, true, true>(lds, gt, S, E, wid0);
.LBB0_822:
	s_andn2_b64 vcc, exec, s[2:3]
	s_cbranch_vccnz .LBB0_924
	s_mov_b64 s[2:3], s[88:89]
	s_load_dwordx2 s[2:3], s[2:3], 0x98
	s_waitcnt lgkmcnt(0)
	s_add_u32 s4, s2, 0x10e74000
	s_addc_u32 s5, s3, 0
	s_andn2_b64 vcc, exec, s[24:25]
	s_cbranch_vccnz .LBB0_825
	v_readlane_b32 s4, v255, 36
	v_readlane_b32 s5, v255, 37
	s_add_u32 s1, s1, s4
	s_addc_u32 s6, s6, s5
	s_add_u32 s12, s12, s4
	s_addc_u32 s13, s13, s5
	v_readlane_b32 s4, v255, 9
	v_readlane_b32 s5, v255, 10
	s_add_u32 s4, s2, s4
	s_addc_u32 s5, s3, s5
	s_add_u32 s4, s4, 0xfc200000
	s_addc_u32 s5, s5, -1
	s_lshr_b32 s14, s33, 3
	s_lshl_b32 s14, s14, 7
	s_sub_i32 s14, 0x300, s14
	s_branch .LBB0_826

; __device__ __forceinline__ KP kp_fresh(KP k) { asm volatile("" : "+s"(k)); return k; }
; __device__ __forceinline__ int tid_fresh(int wid) { return wid * 64 + lane_id(); }
; __device__ __forceinline__ void row_res(KP kp, int gpost_in, int layer, bool has_next, int wid0, int row0, int row1, int b0, int nb, int tailp, bool pooled) {
;     kp = kp_fresh(kp); const int tid = tid_fresh(wid0); const int lane = tid & 63, wid = tid >> 6;
;     unsigned char* ws = kp->ws; float* out = kp->out; const bf16* MX = (const bf16*)(ws + WS_MX); float* rsd = (float*)(ws + WS_RSTD);
;     const float* g_post = kp->in[gpost_in] + layer * DM;
;     for (int base = row0 + ((int)blockIdx.x - b0) * 16 + wid; base < row1; base += nb * 16) {
; __global__ void __launch_bounds__(512, 2) hybrid_fwd(Params p_unused) {
;     ...
;                 const int rpb = 256 / ntail;
;                 row_res(kp0, gpi, layer, hn, wid0, 128 * 256 + rpb * bid, 128 * 256 + rpb * bid + rpb, bid, 1, half == 1 ? 2 : 0, half == 0 && (layer & 1));
.LBB0_860:
	s_or_b64 exec, exec, s[2:3]
	s_mov_b64 s[2:3], s[88:89]
	s_barrier
	s_and_b64 s[0:1], s[24:25], exec
	v_mbcnt_lo_u32_b32 v1, -1, 0
	v_mbcnt_hi_u32_b32 v1, -1, v1
	s_cselect_b32 s0, 16, 64
	v_add_u32_e32 v2, s61, v1
	v_ashrrev_i32_e32 v2, 6, v2
	v_cmp_gt_i32_e32 vcc, s0, v2
	s_and_saveexec_b64 s[36:37], vcc
	s_cbranch_execz .LBB0_923
	s_and_b64 s[4:5], s[24:25], exec
	s_load_dwordx4 s[8:11], s[2:3], 0x90
	s_cselect_b32 s1, 4, 6
	v_readlane_b32 s4, v255, 51
	s_lshl_b32 s1, s33, s1
	v_readlane_b32 s5, v255, 52
	s_add_i32 s6, s1, 0x8000
	s_and_b64 s[4:5], s[4:5], s[28:29]
	s_add_i32 s0, s6, s0
	s_xor_b64 s[28:29], s[4:5], -1
	s_waitcnt lgkmcnt(0)
	s_add_u32 s44, s10, 0x180000
	s_addc_u32 s45, s11, 0
	s_lshl_b32 s4, s17, 3
	s_load_dwordx2 s[2:3], s[2:3], s4 offset:0x0
	v_readlane_b32 s4, v255, 53
	v_readlane_b32 s5, v255, 54
	s_lshl_b64 s[4:5], s[4:5], 2
	v_and_b32_e32 v3, 63, v1
	s_waitcnt lgkmcnt(0)
	s_add_u32 s4, s2, s4
	v_lshlrev_b32_e32 v4, 4, v3
	v_mov_b32_e32 v5, v0
	s_addc_u32 s5, s3, s5
	v_lshl_add_u64 v[6:7], s[10:11], 0, v[4:5]
	s_mov_b64 s[2:3], 0x18f74000
	v_lshl_add_u64 v[42:43], v[6:7], 0, s[2:3]
	s_mov_b64 s[2:3], 0x200000
	v_lshl_add_u64 v[44:45], v[6:7], 0, s[2:3]
	s_mov_b64 s[2:3], 0x10e74000
	v_lshl_add_u64 v[46:47], v[6:7], 0, s[2:3]
	v_bfe_u32 v6, v1, 5, 1
	v_lshlrev_b32_e64 v1, v6, 2
	v_lshlrev_b32_e64 v41, v6, 8
	v_lshlrev_b32_e32 v6, 2, v3
	v_xor_b32_e32 v103, 0x80, v6
	v_xor_b32_e32 v104, 64, v6
	v_xor_b32_e32 v105, 32, v6
	v_xor_b32_e32 v106, 16, v6
	v_xor_b32_e32 v107, 8, v6
	v_xor_b32_e32 v108, 4, v6
	v_lshlrev_b32_e32 v6, 5, v3
	v_mov_b32_e32 v7, v0
	v_add_u32_e32 v38, s6, v2
	v_lshl_add_u64 v[48:49], s[4:5], 0, v[6:7]
	s_add_u32 s4, s10, 0x10e73800
	s_addc_u32 s5, s11, 0
	v_ashrrev_i32_e32 v39, 31, v38
	v_lshlrev_b64 v[6:7], 11, v[38:39]
	s_add_u32 s6, s10, 0x10e73c00
	v_or_b32_e32 v6, v6, v4
	s_addc_u32 s7, s11, 0
	v_add_u32_e32 v2, s1, v2
	v_lshlrev_b32_e32 v40, 3, v3
	v_cmp_eq_u32_e64 s[2:3], 0, v3
	v_lshl_add_u64 v[50:51], s[4:5], 0, v[6:7]
	v_lshl_add_u64 v[52:53], s[6:7], 0, v[6:7]
	v_lshl_add_u64 v[54:55], s[4:5], 0, v[4:5]
	v_add_u32_e32 v56, 0x8008, v2
	v_lshl_add_u64 v[58:59], s[6:7], 0, v[4:5]
	s_mov_b64 s[10:11], 0
	s_branch .LBB0_864

; __device__ __forceinline__ void unpack8(const u32x4 w, float* v) { v[0] = bflo(w.x); v[1] = bfhi(w.x); v[2] = bflo(w.y); v[3] = bfhi(w.y); v[4] = bflo(w.z); v[5] = bfhi(w.z); v[6] = bflo(w.w); v[7] = bfhi(w.w); }
; __device__ __forceinline__ void row_res(KP kp, int gpost_in, int layer, bool has_next, int wid0, int row0, int row1, int b0, int nb, int tailp, bool pooled) {
;     ...
;                 if (tailp) { const bf16* t0 = (const bf16*)(ws + WS_MXT) + (size_t)(row - 128 * 256) * DM + c * 512 + lane * 8; unpack8(*(const u32x4*)t0, m[r][c]);
;                     for (int q = 1; q < tailp; ++q) { float m2[8]; unpack8(*(const u32x4*)(t0 + (size_t)q * 256 * 1024), m2);
; #pragma unroll
;                         for (int j = 0; j < 8; ++j) m[r][c][j] += m2[j]; } }
.Ltl_tailp:
	v_lshl_add_u64 v[170:171], v[44:45], 0, v[2:3]
	s_mov_b32 s94, 0xfc000000
	s_mov_b32 s95, -1
	v_lshl_add_u64 v[170:171], v[170:171], 0, s[94:95]
	s_mov_b64 s[94:95], 0x80000
	v_lshl_add_u64 v[172:173], v[170:171], 0, s[94:95]
	global_load_dwordx4 v[118:121], v[170:171], off
	global_load_dwordx4 v[122:125], v[170:171], off offset:1024
	global_load_dwordx4 v[134:137], v[172:173], off
	global_load_dwordx4 v[138:141], v[172:173], off offset:1024
	s_mov_b64 s[94:95], 0x4000
	v_lshl_add_u64 v[170:171], v[170:171], 0, s[94:95]
	v_lshl_add_u64 v[172:173], v[172:173], 0, s[94:95]
	global_load_dwordx4 v[126:129], v[170:171], off
	global_load_dwordx4 v[130:133], v[170:171], off offset:1024
	global_load_dwordx4 v[142:145], v[172:173], off
	global_load_dwordx4 v[146:149], v[172:173], off offset:1024
	s_mov_b64 s[94:95], 0x80000
	v_lshl_add_u64 v[236:237], v[172:173], 0, s[94:95]
	v_lshl_add_u64 v[238:239], v[236:237], 0, s[94:95]
	global_load_dwordx4 v[182:185], v[236:237], off
	global_load_dwordx4 v[186:189], v[236:237], off offset:1024
	global_load_dwordx4 v[198:201], v[238:239], off
	global_load_dwordx4 v[202:205], v[238:239], off offset:1024
	s_mov_b32 s94, 0xffffc000
	s_mov_b32 s95, -1
	v_lshl_add_u64 v[236:237], v[236:237], 0, s[94:95]
	v_lshl_add_u64 v[238:239], v[238:239], 0, s[94:95]
	global_load_dwordx4 v[174:177], v[236:237], off
	global_load_dwordx4 v[178:181], v[236:237], off offset:1024
	global_load_dwordx4 v[190:193], v[238:239], off
	global_load_dwordx4 v[194:197], v[238:239], off offset:1024

; __device__ __forceinline__ void unpack8(const u32x4 w, float* v) { v[0] = bflo(w.x); v[1] = bfhi(w.x); v[2] = bflo(w.y); v[3] = bfhi(w.y); v[4] = bflo(w.z); v[5] = bfhi(w.z); v[6] = bflo(w.w); v[7] = bfhi(w.w); }
; __device__ __forceinline__ void row_res(KP kp, int gpost_in, int layer, bool has_next, int wid0, int row0, int row1, int b0, int nb, int tailp, bool pooled) {
;     ...
;                 if (tailp) { const bf16* t0 = (const bf16*)(ws + WS_MXT) + (size_t)(row - 128 * 256) * DM + c * 512 + lane * 8; unpack8(*(const u32x4*)t0, m[r][c]);
;                     for (int q = 1; q < tailp; ++q) { float m2[8]; unpack8(*(const u32x4*)(t0 + (size_t)q * 256 * 1024), m2);
; #pragma unroll
;                         for (int j = 0; j < 8; ++j) m[r][c][j] += m2[j]; } }
.LBB0_874:
	s_andn2_b64 vcc, exec, s[4:5]
	s_brev_b32 s4, 63
	v_lshl_add_u64 v[10:11], v[44:45], 0, v[2:3]
	s_mov_b32 s5, -1
	v_lshl_add_u64 v[8:9], v[10:11], 0, s[4:5]
	s_cbranch_vccnz .LBB0_876
	v_add_co_u32_e32 v4, vcc, 0x80000, v8
	s_waitcnt vmcnt(0)
	v_mov_b64_e32 v[12:13], v[118:119]
	v_mov_b64_e32 v[14:15], v[120:121]
	s_nop 0
	v_addc_co_u32_e32 v5, vcc, 0, v9, vcc
	s_waitcnt vmcnt(0)
	v_mov_b64_e32 v[18:19], v[134:135]
	v_mov_b64_e32 v[20:21], v[136:137]
	s_waitcnt vmcnt(1)
	v_lshlrev_b32_e32 v4, 16, v12
	v_and_b32_e32 v5, 0xffff0000, v12
	s_waitcnt vmcnt(0)
	v_lshlrev_b32_e32 v22, 16, v18
	s_waitcnt lgkmcnt(0)
	v_and_b32_e32 v23, 0xffff0000, v18
	v_pk_add_f32 v[22:23], v[4:5], v[22:23]
	v_lshlrev_b32_e32 v4, 16, v13
	v_and_b32_e32 v5, 0xffff0000, v13
	v_lshlrev_b32_e32 v12, 16, v19
	v_and_b32_e32 v13, 0xffff0000, v19
	v_pk_add_f32 v[24:25], v[4:5], v[12:13]
	v_lshlrev_b32_e32 v4, 16, v14
	v_and_b32_e32 v5, 0xffff0000, v14
	v_lshlrev_b32_e32 v12, 16, v20
	v_and_b32_e32 v13, 0xffff0000, v20
	v_pk_add_f32 v[26:27], v[4:5], v[12:13]
	v_lshlrev_b32_e32 v4, 16, v15
	v_and_b32_e32 v5, 0xffff0000, v15
	v_lshlrev_b32_e32 v12, 16, v21
	v_and_b32_e32 v13, 0xffff0000, v21
	v_pk_add_f32 v[28:29], v[4:5], v[12:13]
	v_lshlrev_b32_e32 v4, 16, v174
	v_and_b32_e32 v5, 0xffff0000, v174
	v_pk_add_f32 v[22:23], v[22:23], v[4:5]
	v_lshlrev_b32_e32 v4, 16, v175
	v_and_b32_e32 v5, 0xffff0000, v175
	v_pk_add_f32 v[24:25], v[24:25], v[4:5]
	v_lshlrev_b32_e32 v4, 16, v176
	v_and_b32_e32 v5, 0xffff0000, v176
	v_pk_add_f32 v[26:27], v[26:27], v[4:5]
	v_lshlrev_b32_e32 v4, 16, v177
	v_and_b32_e32 v5, 0xffff0000, v177
	v_pk_add_f32 v[28:29], v[28:29], v[4:5]
	v_lshlrev_b32_e32 v4, 16, v190
	v_and_b32_e32 v5, 0xffff0000, v190
	v_pk_add_f32 v[22:23], v[22:23], v[4:5]
	v_lshlrev_b32_e32 v4, 16, v191
	v_and_b32_e32 v5, 0xffff0000, v191
	v_pk_add_f32 v[24:25], v[24:25], v[4:5]
	v_lshlrev_b32_e32 v4, 16, v192
	v_and_b32_e32 v5, 0xffff0000, v192
	v_pk_add_f32 v[26:27], v[26:27], v[4:5]
	v_lshlrev_b32_e32 v4, 16, v193
	v_and_b32_e32 v5, 0xffff0000, v193
	v_pk_add_f32 v[28:29], v[28:29], v[4:5]

; __device__ __forceinline__ void unpack8(const u32x4 w, float* v) { v[0] = bflo(w.x); v[1] = bfhi(w.x); v[2] = bflo(w.y); v[3] = bfhi(w.y); v[4] = bflo(w.z); v[5] = bfhi(w.z); v[6] = bflo(w.w); v[7] = bfhi(w.w); }
; __device__ __forceinline__ void row_res(KP kp, int gpost_in, int layer, bool has_next, int wid0, int row0, int row1, int b0, int nb, int tailp, bool pooled) {
;     ...
;                 if (tailp) { const bf16* t0 = (const bf16*)(ws + WS_MXT) + (size_t)(row - 128 * 256) * DM + c * 512 + lane * 8; unpack8(*(const u32x4*)t0, m[r][c]);
;                     for (int q = 1; q < tailp; ++q) { float m2[8]; unpack8(*(const u32x4*)(t0 + (size_t)q * 256 * 1024), m2);
; #pragma unroll
;                         for (int j = 0; j < 8; ++j) m[r][c][j] += m2[j]; } }
.LBB0_886:
	s_andn2_b64 vcc, exec, s[14:15]
	s_cbranch_vccnz .LBB0_888
	v_add_co_u32_e32 v6, vcc, 0x80000, v8
	s_waitcnt vmcnt(0)
	v_mov_b64_e32 v[12:13], v[122:123]
	v_mov_b64_e32 v[14:15], v[124:125]
	s_nop 0
	v_addc_co_u32_e32 v7, vcc, 0, v9, vcc
	s_waitcnt vmcnt(0)
	v_mov_b64_e32 v[6:7], v[138:139]
	v_mov_b64_e32 v[8:9], v[140:141]
	s_waitcnt vmcnt(1)
	v_lshlrev_b32_e32 v16, 16, v12
	v_and_b32_e32 v17, 0xffff0000, v12
	v_lshlrev_b32_e32 v12, 16, v13
	s_waitcnt vmcnt(0)
	v_lshlrev_b32_e32 v18, 16, v6
	v_and_b32_e32 v19, 0xffff0000, v6
	v_and_b32_e32 v13, 0xffff0000, v13
	v_lshlrev_b32_e32 v6, 16, v7
	v_and_b32_e32 v7, 0xffff0000, v7
	v_pk_add_f32 v[32:33], v[12:13], v[6:7]
	v_lshlrev_b32_e32 v6, 16, v14
	v_and_b32_e32 v7, 0xffff0000, v14
	v_lshlrev_b32_e32 v12, 16, v8
	v_and_b32_e32 v13, 0xffff0000, v8
	v_pk_add_f32 v[34:35], v[6:7], v[12:13]
	v_lshlrev_b32_e32 v6, 16, v15
	v_and_b32_e32 v7, 0xffff0000, v15
	v_lshlrev_b32_e32 v8, 16, v9
	v_and_b32_e32 v9, 0xffff0000, v9
	v_pk_add_f32 v[30:31], v[16:17], v[18:19]
	v_pk_add_f32 v[36:37], v[6:7], v[8:9]
	v_lshlrev_b32_e32 v6, 16, v178
	v_and_b32_e32 v7, 0xffff0000, v178
	v_pk_add_f32 v[30:31], v[30:31], v[6:7]
	v_lshlrev_b32_e32 v6, 16, v179
	v_and_b32_e32 v7, 0xffff0000, v179
	v_pk_add_f32 v[32:33], v[32:33], v[6:7]
	v_lshlrev_b32_e32 v6, 16, v180
	v_and_b32_e32 v7, 0xffff0000, v180
	v_pk_add_f32 v[34:35], v[34:35], v[6:7]
	v_lshlrev_b32_e32 v6, 16, v181
	v_and_b32_e32 v7, 0xffff0000, v181
	v_pk_add_f32 v[36:37], v[36:37], v[6:7]
	v_lshlrev_b32_e32 v6, 16, v194
	v_and_b32_e32 v7, 0xffff0000, v194
	v_pk_add_f32 v[30:31], v[30:31], v[6:7]
	v_lshlrev_b32_e32 v6, 16, v195
	v_and_b32_e32 v7, 0xffff0000, v195
	v_pk_add_f32 v[32:33], v[32:33], v[6:7]
	v_lshlrev_b32_e32 v6, 16, v196
	v_and_b32_e32 v7, 0xffff0000, v196
	v_pk_add_f32 v[34:35], v[34:35], v[6:7]
	v_lshlrev_b32_e32 v6, 16, v197
	v_and_b32_e32 v7, 0xffff0000, v197
	v_pk_add_f32 v[36:37], v[36:37], v[6:7]

; __device__ __forceinline__ void unpack8(const u32x4 w, float* v) { v[0] = bflo(w.x); v[1] = bfhi(w.x); v[2] = bflo(w.y); v[3] = bfhi(w.y); v[4] = bflo(w.z); v[5] = bfhi(w.z); v[6] = bflo(w.w); v[7] = bfhi(w.w); }
; __device__ __forceinline__ void row_res(KP kp, int gpost_in, int layer, bool has_next, int wid0, int row0, int row1, int b0, int nb, int tailp, bool pooled) {
;     ...
;                 if (tailp) { const bf16* t0 = (const bf16*)(ws + WS_MXT) + (size_t)(row - 128 * 256) * DM + c * 512 + lane * 8; unpack8(*(const u32x4*)t0, m[r][c]);
;                     for (int q = 1; q < tailp; ++q) { float m2[8]; unpack8(*(const u32x4*)(t0 + (size_t)q * 256 * 1024), m2);
; #pragma unroll
;                         for (int j = 0; j < 8; ++j) m[r][c][j] += m2[j]; } }
.LBB0_898:
	s_mov_b32 s6, 0xfc004000
	s_mov_b32 s7, -1
	s_andn2_b64 vcc, exec, s[14:15]
	v_lshl_add_u64 v[18:19], v[10:11], 0, s[6:7]
	s_cbranch_vccnz .LBB0_900
	v_add_co_u32_e32 v10, vcc, 0x80000, v18
	s_waitcnt vmcnt(0)
	v_mov_b64_e32 v[72:73], v[126:127]
	v_mov_b64_e32 v[74:75], v[128:129]
	s_nop 0
	v_addc_co_u32_e32 v11, vcc, 0, v19, vcc
	s_waitcnt vmcnt(0)
	v_mov_b64_e32 v[76:77], v[142:143]
	v_mov_b64_e32 v[78:79], v[144:145]
	s_waitcnt vmcnt(1)
	v_lshlrev_b32_e32 v10, 16, v72
	v_and_b32_e32 v11, 0xffff0000, v72
	s_waitcnt vmcnt(0)
	v_lshlrev_b32_e32 v20, 16, v76
	v_and_b32_e32 v21, 0xffff0000, v76
	v_pk_add_f32 v[68:69], v[10:11], v[20:21]
	v_lshlrev_b32_e32 v10, 16, v73
	v_and_b32_e32 v11, 0xffff0000, v73
	v_lshlrev_b32_e32 v20, 16, v77
	v_and_b32_e32 v21, 0xffff0000, v77
	v_pk_add_f32 v[70:71], v[10:11], v[20:21]
	v_lshlrev_b32_e32 v10, 16, v74
	v_and_b32_e32 v11, 0xffff0000, v74
	v_lshlrev_b32_e32 v20, 16, v78
	v_and_b32_e32 v21, 0xffff0000, v78
	v_pk_add_f32 v[72:73], v[10:11], v[20:21]
	v_lshlrev_b32_e32 v10, 16, v75
	v_and_b32_e32 v11, 0xffff0000, v75
	v_lshlrev_b32_e32 v20, 16, v79
	v_and_b32_e32 v21, 0xffff0000, v79
	v_pk_add_f32 v[74:75], v[10:11], v[20:21]
	v_lshlrev_b32_e32 v10, 16, v182
	v_and_b32_e32 v11, 0xffff0000, v182
	v_pk_add_f32 v[68:69], v[68:69], v[10:11]
	v_lshlrev_b32_e32 v10, 16, v183
	v_and_b32_e32 v11, 0xffff0000, v183
	v_pk_add_f32 v[70:71], v[70:71], v[10:11]
	v_lshlrev_b32_e32 v10, 16, v184
	v_and_b32_e32 v11, 0xffff0000, v184
	v_pk_add_f32 v[72:73], v[72:73], v[10:11]
	v_lshlrev_b32_e32 v10, 16, v185
	v_and_b32_e32 v11, 0xffff0000, v185
	v_pk_add_f32 v[74:75], v[74:75], v[10:11]
	v_lshlrev_b32_e32 v10, 16, v198
	v_and_b32_e32 v11, 0xffff0000, v198
	v_pk_add_f32 v[68:69], v[68:69], v[10:11]
	v_lshlrev_b32_e32 v10, 16, v199
	v_and_b32_e32 v11, 0xffff0000, v199
	v_pk_add_f32 v[70:71], v[70:71], v[10:11]
	v_lshlrev_b32_e32 v10, 16, v200
	v_and_b32_e32 v11, 0xffff0000, v200
	v_pk_add_f32 v[72:73], v[72:73], v[10:11]
	v_lshlrev_b32_e32 v10, 16, v201
	v_and_b32_e32 v11, 0xffff0000, v201
	v_pk_add_f32 v[74:75], v[74:75], v[10:11]

; __device__ __forceinline__ void unpack8(const u32x4 w, float* v) { v[0] = bflo(w.x); v[1] = bfhi(w.x); v[2] = bflo(w.y); v[3] = bfhi(w.y); v[4] = bflo(w.z); v[5] = bfhi(w.z); v[6] = bflo(w.w); v[7] = bfhi(w.w); }
; __device__ __forceinline__ void row_res(KP kp, int gpost_in, int layer, bool has_next, int wid0, int row0, int row1, int b0, int nb, int tailp, bool pooled) {
;     ...
;                 if (tailp) { const bf16* t0 = (const bf16*)(ws + WS_MXT) + (size_t)(row - 128 * 256) * DM + c * 512 + lane * 8; unpack8(*(const u32x4*)t0, m[r][c]);
;                     for (int q = 1; q < tailp; ++q) { float m2[8]; unpack8(*(const u32x4*)(t0 + (size_t)q * 256 * 1024), m2);
; #pragma unroll
;                         for (int j = 0; j < 8; ++j) m[r][c][j] += m2[j]; } }
.LBB0_910:
	s_andn2_b64 vcc, exec, s[14:15]
	s_cbranch_vccnz .LBB0_912
	s_waitcnt vmcnt(0)
	v_mov_b64_e32 v[14:15], v[130:131]
	v_mov_b64_e32 v[16:17], v[132:133]
	v_add_co_u32_e32 v18, vcc, 0x80000, v18
	s_waitcnt vmcnt(0)
	v_lshlrev_b32_e32 v78, 16, v14
	v_addc_co_u32_e32 v19, vcc, 0, v19, vcc
	s_waitcnt vmcnt(0)
	v_mov_b64_e32 v[18:19], v[146:147]
	v_mov_b64_e32 v[20:21], v[148:149]
	v_and_b32_e32 v79, 0xffff0000, v14
	v_lshlrev_b32_e32 v14, 16, v15
	v_and_b32_e32 v15, 0xffff0000, v15
	s_waitcnt vmcnt(0)
	v_lshlrev_b32_e32 v80, 16, v18
	v_and_b32_e32 v81, 0xffff0000, v18
	v_lshlrev_b32_e32 v18, 16, v19
	v_and_b32_e32 v19, 0xffff0000, v19
	v_pk_add_f32 v[78:79], v[78:79], v[80:81]
	v_pk_add_f32 v[80:81], v[14:15], v[18:19]
	v_lshlrev_b32_e32 v14, 16, v16
	v_and_b32_e32 v15, 0xffff0000, v16
	v_lshlrev_b32_e32 v18, 16, v20
	v_and_b32_e32 v19, 0xffff0000, v20
	v_pk_add_f32 v[82:83], v[14:15], v[18:19]
	v_lshlrev_b32_e32 v14, 16, v17
	v_and_b32_e32 v15, 0xffff0000, v17
	v_lshlrev_b32_e32 v16, 16, v21
	v_and_b32_e32 v17, 0xffff0000, v21
	v_pk_add_f32 v[84:85], v[14:15], v[16:17]
	v_lshlrev_b32_e32 v14, 16, v186
	v_and_b32_e32 v15, 0xffff0000, v186
	v_pk_add_f32 v[78:79], v[78:79], v[14:15]
	v_lshlrev_b32_e32 v14, 16, v187
	v_and_b32_e32 v15, 0xffff0000, v187
	v_pk_add_f32 v[80:81], v[80:81], v[14:15]
	v_lshlrev_b32_e32 v14, 16, v188
	v_and_b32_e32 v15, 0xffff0000, v188
	v_pk_add_f32 v[82:83], v[82:83], v[14:15]
	v_lshlrev_b32_e32 v14, 16, v189
	v_and_b32_e32 v15, 0xffff0000, v189
	v_pk_add_f32 v[84:85], v[84:85], v[14:15]
	v_lshlrev_b32_e32 v14, 16, v202
	v_and_b32_e32 v15, 0xffff0000, v202
	v_pk_add_f32 v[78:79], v[78:79], v[14:15]
	v_lshlrev_b32_e32 v14, 16, v203
	v_and_b32_e32 v15, 0xffff0000, v203
	v_pk_add_f32 v[80:81], v[80:81], v[14:15]
	v_lshlrev_b32_e32 v14, 16, v204
	v_and_b32_e32 v15, 0xffff0000, v204
	v_pk_add_f32 v[82:83], v[82:83], v[14:15]
	v_lshlrev_b32_e32 v14, 16, v205
	v_and_b32_e32 v15, 0xffff0000, v205
	v_pk_add_f32 v[84:85], v[84:85], v[14:15]
